# v86 + phase_f row loop: all 16 loads of a row issued up front (global_*), counted wait for Y2, one wait per half instead of eight serial round trips
# speedup vs baseline: 1.0214x; 1.0085x over previous
; DI float bflo(unsigned u) { return __uint_as_float(u << 16); }
; DI float bfhi(unsigned u) { return __uint_as_float(u & 0xffff0000u); }
; DI void phase_f(const Params& P, int hb, int l) {
;     ...
;     for (int row = blockIdx.x * NWAVE + wid; row < HT; row += gridDim.x * NWAVE) {
;         const int grow = hb * HT + row; const int b = grow / SEQ;
;         const u32x2* yr = (const u32x2*)(Y2 + (size_t)row * DM);
;         const f32x4* xr = (const f32x4*)(xin_base + (size_t)grow * DM);
;         f32x4 v[4], xv[4]; float ss = 0.f;
; #pragma unroll
;         for (int j = 0; j < 4; ++j) { const u32x2 yy = yr[lane + 64 * j]; v[j].x = bflo(yy.x); v[j].y = bfhi(yy.x); v[j].z = bflo(yy.y); v[j].w = bfhi(yy.y);
;             xv[j] = xr[lane + 64 * j]; ss += v[j].x * v[j].x + v[j].y * v[j].y + v[j].z * v[j].z + v[j].w * v[j].w; }
;         const float rstd = rsqrtf(wave_sum(ss) * (1.f / DM) + EPS);
;         const f32x4* g = (const f32x4*)(P.g_post + l * DM);
;         const f32x4* gt = (const f32x4*)(mod + (l * 4 + b) * 3072 + 2048);
;         f32x4* orow = (f32x4*)(P.out + (size_t)grow * DM);
;         float ss2 = 0.f;
; #pragma unroll
;         for (int j = 0; j < 4; ++j) {
;             const int c4 = lane + 64 * j; f32x4 gg = g[c4], ga = gt[c4];
;             xv[j].x += ga.x * (v[j].x * rstd * gg.x); xv[j].y += ga.y * (v[j].y * rstd * gg.y);
;             xv[j].z += ga.z * (v[j].z * rstd * gg.z); xv[j].w += ga.w * (v[j].w * rstd * gg.w);
;             orow[c4] = xv[j];
;             ss2 += xv[j].x * xv[j].x + xv[j].y * xv[j].y + xv[j].z * xv[j].z + xv[j].w * xv[j].w;
;         }
.LBB0_450:
	v_ashrrev_i32_e32 v19, 31, v18
	v_lshlrev_b64 v[2:3], 11, v[18:19]
	v_lshl_add_u64 v[2:3], v[32:33], 0, v[2:3]
	global_load_dwordx2 v[14:15], v[2:3], off
	global_load_dwordx2 v[16:17], v[2:3], off offset:512
	global_load_dwordx2 v[50:51], v[2:3], off offset:1024
	global_load_dwordx2 v[52:53], v[2:3], off offset:1536
	v_add_u32_e32 v6, s71, v18
	v_ashrrev_i32_e32 v7, 31, v6
	v_lshlrev_b64 v[58:59], 12, v[6:7]
	v_lshrrev_b32_e32 v7, 19, v7
	v_add_u32_e32 v10, v6, v7
	v_ashrrev_i32_e32 v48, 13, v10
	v_add_u32_e32 v10, s2, v48
	v_mul_i32_i24_e32 v10, 0xc00, v10
	v_ashrrev_i32_e32 v11, 31, v10
	v_lshl_add_u64 v[10:11], v[10:11], 2, s[4:5]
	s_mov_b64 s[8:9], 0x2000
	v_lshlrev_b32_e32 v0, 4, v20
	v_lshl_add_u64 v[66:67], v[10:11], 0, s[8:9]
	v_lshl_add_u64 v[62:63], v[34:35], 0, v[58:59]
	global_load_dwordx4 v[88:91], v[62:63], off
	global_load_dwordx4 v[92:95], v[62:63], off offset:1024
	global_load_dwordx4 v[96:99], v[62:63], off offset:2048
	global_load_dwordx4 v[100:103], v[62:63], off offset:3072
	global_load_dwordx4 v[104:107], v[22:23], off
	global_load_dwordx4 v[108:111], v[22:23], off offset:1024
	global_load_dwordx4 v[112:115], v[22:23], off offset:2048
	global_load_dwordx4 v[116:119], v[22:23], off offset:3072
	v_mov_b32_e32 v41, v1
	v_mov_b32_e32 v43, v1
	v_mov_b32_e32 v45, v1
	v_lshl_add_u64 v[10:11], v[66:67], 0, v[0:1]
	global_load_dwordx4 v[120:123], v[10:11], off
	v_lshl_add_u64 v[10:11], v[66:67], 0, v[40:41]
	global_load_dwordx4 v[124:127], v[10:11], off
	v_lshl_add_u64 v[10:11], v[66:67], 0, v[42:43]
	global_load_dwordx4 v[2:5], v[10:11], off
	v_lshl_add_u64 v[10:11], v[66:67], 0, v[44:45]
	global_load_dwordx4 v[6:9], v[10:11], off
	s_waitcnt vmcnt(12)
	v_and_b32_e32 v71, 0xffff0000, v14
	v_and_b32_e32 v75, 0xffff0000, v16
	v_lshlrev_b32_e32 v70, 16, v14
	v_lshlrev_b32_e32 v74, 16, v16
	v_and_b32_e32 v79, 0xffff0000, v50
	v_lshlrev_b32_e32 v80, 16, v53
	v_and_b32_e32 v81, 0xffff0000, v53
	v_lshlrev_b32_e32 v82, 16, v52
	v_and_b32_e32 v83, 0xffff0000, v52
	v_mov_b32_e32 v52, v71
	v_mov_b32_e32 v53, v75
	v_lshlrev_b32_e32 v68, 16, v15
	v_lshlrev_b32_e32 v72, 16, v17
	v_lshlrev_b32_e32 v76, 16, v51
	v_and_b32_e32 v77, 0xffff0000, v51
	v_lshlrev_b32_e32 v78, 16, v50
	v_mov_b32_e32 v50, v70
	v_mov_b32_e32 v51, v74
	v_mov_b32_e32 v86, v79
	v_mov_b32_e32 v87, v83
	v_pk_mul_f32 v[52:53], v[52:53], v[52:53]
	v_and_b32_e32 v69, 0xffff0000, v15
	v_and_b32_e32 v73, 0xffff0000, v17
	v_mov_b32_e32 v14, v68
	v_mov_b32_e32 v15, v72
	v_mov_b32_e32 v84, v78
	v_mov_b32_e32 v85, v82
	v_pk_mul_f32 v[86:87], v[86:87], v[86:87]
	v_pk_fma_f32 v[50:51], v[50:51], v[50:51], v[52:53]
	v_mov_b32_e32 v16, v69
	v_mov_b32_e32 v17, v73
	v_mov_b32_e32 v60, v76
	v_mov_b32_e32 v61, v80
	v_pk_fma_f32 v[52:53], v[84:85], v[84:85], v[86:87]
	v_pk_fma_f32 v[14:15], v[14:15], v[14:15], v[50:51]
	v_mov_b32_e32 v64, v77
	v_mov_b32_e32 v65, v81
	v_pk_fma_f32 v[50:51], v[60:61], v[60:61], v[52:53]
	v_pk_fma_f32 v[14:15], v[16:17], v[16:17], v[14:15]
	v_pk_fma_f32 v[16:17], v[64:65], v[64:65], v[50:51]
	v_add_f32_e32 v14, v14, v15
	v_add_f32_e32 v14, v14, v16
	v_add_f32_e32 v14, v14, v17
	ds_bpermute_b32 v15, v21, v14
	v_lshl_add_u64 v[84:85], v[36:37], 0, v[58:59]
	s_waitcnt lgkmcnt(0)
	v_add_f32_e32 v14, v14, v15
	ds_bpermute_b32 v15, v47, v14
	s_waitcnt lgkmcnt(0)
	v_add_f32_e32 v14, v14, v15
	ds_bpermute_b32 v15, v54, v14
	s_waitcnt lgkmcnt(0)
	v_add_f32_e32 v14, v14, v15
	ds_bpermute_b32 v15, v55, v14
	s_waitcnt lgkmcnt(0)
	v_add_f32_e32 v14, v14, v15
	ds_bpermute_b32 v15, v56, v14
	s_waitcnt lgkmcnt(0)
	v_add_f32_e32 v14, v14, v15
	ds_bpermute_b32 v15, v57, v14
	s_waitcnt lgkmcnt(0)
	v_add_f32_e32 v14, v14, v15
	v_fmamk_f32 v14, v14, 0x3a800000, v175
	v_mul_f32_e32 v15, 0x4b800000, v14
	v_cmp_gt_f32_e32 vcc, s66, v14
	s_nop 1
	v_cndmask_b32_e32 v14, v14, v15, vcc
	v_rsq_f32_e32 v14, v14
	s_nop 0
	v_mul_f32_e32 v15, 0x45800000, v14
	v_cndmask_b32_e32 v46, v14, v15, vcc
	s_andn2_b64 vcc, exec, s[14:15]
	s_waitcnt vmcnt(0)
	v_pk_mul_f32 v[10:11], v[46:47], v[70:71] op_sel_hi:[0,1]
	v_pk_mul_f32 v[12:13], v[46:47], v[68:69] op_sel_hi:[0,1]
	v_pk_mul_f32 v[58:59], v[46:47], v[74:75] op_sel_hi:[0,1]
	v_pk_mul_f32 v[60:61], v[46:47], v[72:73] op_sel_hi:[0,1]
	v_pk_mul_f32 v[104:105], v[104:105], v[10:11]
	v_pk_mul_f32 v[106:107], v[106:107], v[12:13]
	v_pk_mul_f32 v[108:109], v[108:109], v[58:59]
	v_pk_mul_f32 v[110:111], v[110:111], v[60:61]
	v_pk_fma_f32 v[88:89], v[120:121], v[104:105], v[88:89]
	v_pk_fma_f32 v[90:91], v[122:123], v[106:107], v[90:91]
	v_pk_fma_f32 v[92:93], v[124:125], v[108:109], v[92:93]
	v_pk_fma_f32 v[94:95], v[126:127], v[110:111], v[94:95]
	global_store_dwordx4 v[84:85], v[88:91], off
	global_store_dwordx4 v[84:85], v[92:95], off offset:1024
	v_pk_mul_f32 v[10:11], v[46:47], v[78:79] op_sel_hi:[0,1]
	v_pk_mul_f32 v[12:13], v[46:47], v[76:77] op_sel_hi:[0,1]
	v_pk_mul_f32 v[58:59], v[46:47], v[82:83] op_sel_hi:[0,1]
	v_pk_mul_f32 v[60:61], v[46:47], v[80:81] op_sel_hi:[0,1]
	v_pk_mul_f32 v[112:113], v[112:113], v[10:11]
	v_pk_mul_f32 v[114:115], v[114:115], v[12:13]
	v_pk_mul_f32 v[116:117], v[116:117], v[58:59]
	v_pk_mul_f32 v[118:119], v[118:119], v[60:61]
	v_pk_fma_f32 v[96:97], v[2:3], v[112:113], v[96:97]
	v_pk_fma_f32 v[98:99], v[4:5], v[114:115], v[98:99]
	v_pk_fma_f32 v[100:101], v[6:7], v[116:117], v[100:101]
	v_pk_fma_f32 v[102:103], v[8:9], v[118:119], v[102:103]
	global_store_dwordx4 v[84:85], v[96:99], off offset:2048
	global_store_dwordx4 v[84:85], v[100:103], off offset:3072
	s_cbranch_vccnz .LBB0_449
; DI unsigned pk2(float lo, float hi) { fl2_t f = {lo, hi}; bf2_t b = __builtin_convertvector(f, bf2_t); return __builtin_bit_cast(unsigned, b); }
; DI void phase_f(const Params& P, int hb, int l) {
;     ...
;             ss2 += xv[j].x * xv[j].x + xv[j].y * xv[j].y + xv[j].z * xv[j].z + xv[j].w * xv[j].w;
;         }
;         if (l == 0) {
;             const float rstd2 = rsqrtf(wave_sum(ss2) * (1.f / DM) + EPS);
;             const f32x4* g1 = (const f32x4*)(P.g_pre + DM);
;             const f32x4* sh = (const f32x4*)(mod + (1 * 4 + b) * 3072);
;             const f32x4* sc = (const f32x4*)(mod + (1 * 4 + b) * 3072 + 1024);
;             u32x2* o8 = (u32x2*)(Hh + (size_t)row * DM);
; #pragma unroll
;             for (int j = 0; j < 4; ++j) {
;                 const int c4 = lane + 64 * j; f32x4 gg = g1[c4], s1 = sc[c4], s0 = sh[c4];
;                 float h0 = xv[j].x * rstd2 * gg.x * (1.f + s1.x) + s0.x, h1 = xv[j].y * rstd2 * gg.y * (1.f + s1.y) + s0.y;
;                 float h2 = xv[j].z * rstd2 * gg.z * (1.f + s1.z) + s0.z, h3 = xv[j].w * rstd2 * gg.w * (1.f + s1.w) + s0.w;
;                 u32x2 o = {pk2(h0, h1), pk2(h2, h3)}; o8[c4] = o;
;             }
	v_mul_i32_i24_e32 v48, 0xc00, v48
	v_ashrrev_i32_e32 v49, 31, v48
	v_lshlrev_b64 v[128:129], 10, v[18:19]
	v_lshl_add_u64 v[12:13], v[48:49], 2, s[4:5]
	s_mov_b64 s[8:9], 0xc000
	v_lshl_add_u64 v[10:11], v[12:13], 0, s[8:9]
	s_mov_b64 s[8:9], 0xd000
	v_lshl_add_u64 v[12:13], v[12:13], 0, s[8:9]
	global_load_dwordx4 v[104:107], v[24:25], off
	global_load_dwordx4 v[108:111], v[26:27], off
	global_load_dwordx4 v[112:115], v[28:29], off
	global_load_dwordx4 v[116:119], v[30:31], off
	v_lshl_add_u64 v[58:59], v[12:13], 0, v[0:1]
	global_load_dwordx4 v[120:123], v[58:59], off
	v_lshl_add_u64 v[58:59], v[12:13], 0, v[40:41]
	global_load_dwordx4 v[124:127], v[58:59], off
	v_lshl_add_u64 v[58:59], v[12:13], 0, v[42:43]
	global_load_dwordx4 v[2:5], v[58:59], off
	v_lshl_add_u64 v[58:59], v[12:13], 0, v[44:45]
	global_load_dwordx4 v[6:9], v[58:59], off
	v_lshl_add_u64 v[58:59], v[10:11], 0, v[0:1]
	global_load_dwordx4 v[68:71], v[58:59], off
	v_lshl_add_u64 v[58:59], v[10:11], 0, v[40:41]
	global_load_dwordx4 v[72:75], v[58:59], off
	v_lshl_add_u64 v[58:59], v[10:11], 0, v[42:43]
	global_load_dwordx4 v[76:79], v[58:59], off
	v_lshl_add_u64 v[58:59], v[10:11], 0, v[44:45]
	global_load_dwordx4 v[80:83], v[58:59], off
	v_mov_b32_e32 v62, v89
	v_mov_b32_e32 v63, v93
	v_mov_b32_e32 v60, v88
	v_mov_b32_e32 v61, v92
	v_pk_mul_f32 v[62:63], v[62:63], v[62:63]
	v_mov_b32_e32 v58, v90
	v_mov_b32_e32 v59, v94
	v_pk_fma_f32 v[60:61], v[60:61], v[60:61], v[62:63]
	v_mov_b32_e32 v50, v91
	v_mov_b32_e32 v51, v95
	v_pk_fma_f32 v[58:59], v[58:59], v[58:59], v[60:61]
	v_mov_b32_e32 v64, v101
	v_mov_b32_e32 v65, v97
	v_pk_fma_f32 v[50:51], v[50:51], v[50:51], v[58:59]
	v_mov_b32_e32 v62, v100
	v_mov_b32_e32 v63, v96
	v_pk_mul_f32 v[64:65], v[64:65], v[64:65]
	v_mov_b32_e32 v60, v102
	v_mov_b32_e32 v61, v98
	v_pk_fma_f32 v[62:63], v[62:63], v[62:63], v[64:65]
	v_add_f32_e32 v19, v50, v51
	v_mov_b32_e32 v58, v103
	v_mov_b32_e32 v59, v99
	v_pk_fma_f32 v[60:61], v[60:61], v[60:61], v[62:63]
	v_pk_fma_f32 v[58:59], v[58:59], v[58:59], v[60:61]
	v_add_f32_e32 v19, v59, v19
	v_add_f32_e32 v19, v58, v19
	ds_bpermute_b32 v46, v21, v19
	s_waitcnt lgkmcnt(0)
	v_add_f32_e32 v19, v19, v46
	ds_bpermute_b32 v46, v47, v19
	s_waitcnt lgkmcnt(0)
	v_add_f32_e32 v19, v19, v46
	ds_bpermute_b32 v46, v54, v19
	s_waitcnt lgkmcnt(0)
	v_add_f32_e32 v19, v19, v46
	ds_bpermute_b32 v46, v55, v19
	s_waitcnt lgkmcnt(0)
	v_add_f32_e32 v19, v19, v46
	ds_bpermute_b32 v46, v56, v19
	s_waitcnt lgkmcnt(0)
	v_add_f32_e32 v19, v19, v46
	ds_bpermute_b32 v46, v57, v19
	s_waitcnt lgkmcnt(0)
	v_add_f32_e32 v19, v19, v46
	v_fmamk_f32 v19, v19, 0x3a800000, v175
	v_cmp_gt_f32_e32 vcc, s66, v19
	v_mul_f32_e32 v46, 0x4b800000, v19
	s_nop 0
	v_cndmask_b32_e32 v19, v19, v46, vcc
	v_rsq_f32_e32 v19, v19
	s_nop 0
	v_mul_f32_e32 v46, 0x45800000, v19
	v_cndmask_b32_e32 v46, v19, v46, vcc
	v_pk_mul_f32 v[88:89], v[88:89], v[46:47] op_sel_hi:[1,0]
	v_pk_mul_f32 v[90:91], v[90:91], v[46:47] op_sel_hi:[1,0]
	v_pk_mul_f32 v[92:93], v[92:93], v[46:47] op_sel_hi:[1,0]
	v_pk_mul_f32 v[94:95], v[94:95], v[46:47] op_sel_hi:[1,0]
	v_pk_mul_f32 v[96:97], v[96:97], v[46:47] op_sel_hi:[1,0]
	v_pk_mul_f32 v[98:99], v[98:99], v[46:47] op_sel_hi:[1,0]
	v_pk_mul_f32 v[100:101], v[100:101], v[46:47] op_sel_hi:[1,0]
	v_pk_mul_f32 v[102:103], v[102:103], v[46:47] op_sel_hi:[1,0]
	s_waitcnt vmcnt(0)
	v_pk_mul_f32 v[88:89], v[104:105], v[88:89]
	v_pk_mul_f32 v[90:91], v[106:107], v[90:91]
	v_pk_mul_f32 v[92:93], v[108:109], v[92:93]
	v_pk_mul_f32 v[94:95], v[110:111], v[94:95]
	v_pk_mul_f32 v[96:97], v[112:113], v[96:97]
	v_pk_mul_f32 v[98:99], v[114:115], v[98:99]
	v_pk_mul_f32 v[100:101], v[116:117], v[100:101]
	v_pk_mul_f32 v[102:103], v[118:119], v[102:103]
	v_pk_add_f32 v[120:121], v[120:121], 1.0 op_sel_hi:[1,0]
	v_pk_add_f32 v[122:123], v[122:123], 1.0 op_sel_hi:[1,0]
	v_pk_add_f32 v[124:125], v[124:125], 1.0 op_sel_hi:[1,0]
	v_pk_add_f32 v[126:127], v[126:127], 1.0 op_sel_hi:[1,0]
	v_pk_add_f32 v[2:3], v[2:3], 1.0 op_sel_hi:[1,0]
	v_pk_add_f32 v[4:5], v[4:5], 1.0 op_sel_hi:[1,0]
	v_pk_add_f32 v[6:7], v[6:7], 1.0 op_sel_hi:[1,0]
	v_pk_add_f32 v[8:9], v[8:9], 1.0 op_sel_hi:[1,0]
	v_pk_fma_f32 v[88:89], v[120:121], v[88:89], v[68:69]
	v_pk_fma_f32 v[90:91], v[122:123], v[90:91], v[70:71]
	v_pk_fma_f32 v[92:93], v[124:125], v[92:93], v[72:73]
	v_pk_fma_f32 v[94:95], v[126:127], v[94:95], v[74:75]
	v_pk_fma_f32 v[96:97], v[2:3], v[96:97], v[76:77]
	v_pk_fma_f32 v[98:99], v[4:5], v[98:99], v[78:79]
	v_pk_fma_f32 v[100:101], v[6:7], v[100:101], v[80:81]
	v_pk_fma_f32 v[102:103], v[8:9], v[102:103], v[82:83]
	v_lshl_add_u64 v[14:15], v[128:129], 1, v[38:39]
	v_cvt_pk_bf16_f32 v58, v88, v89
	v_cvt_pk_bf16_f32 v59, v90, v91
	v_cvt_pk_bf16_f32 v60, v92, v93
	v_cvt_pk_bf16_f32 v61, v94, v95
	v_cvt_pk_bf16_f32 v62, v96, v97
	v_cvt_pk_bf16_f32 v63, v98, v99
	v_cvt_pk_bf16_f32 v64, v100, v101
	v_cvt_pk_bf16_f32 v65, v102, v103
	global_store_dwordx2 v[14:15], v[58:59], off
	global_store_dwordx2 v[14:15], v[60:61], off offset:512
	global_store_dwordx2 v[14:15], v[62:63], off offset:1024
	global_store_dwordx2 v[14:15], v[64:65], off offset:1536
	s_branch .LBB0_449
